# V^T epilogue: the four column-sum loads issued together (were 4 serialized load+vmcnt(0)); next tile's row sums prefetched before the K loop instead of a vmcnt(0) drain after the epilogue
# speedup vs baseline: 1.0405x; 1.0405x over previous
; __device__ __forceinline__ float rs_from_ss(float ss) { return rsqrtf(ss * (1.0f / DM) + RMS_EPS); }
; __device__ __forceinline__ void gemm_phase(LAS unsigned char* lds, const Gemm g, const StaticOrder& S, const Epi& E) {
;     ...
;         const bool has_next = S.next(ui + 1, nxt);
;     ...
;         if (rowss && cur.pm != cached_pm) { const float* sp = E.ss_in + cur.pm * BM + wr * 64 + lane; const float a_ = sp[0], b_ = sp[HALF]; rsl[lane] = rs_from_ss(a_); rsl[64 + lane] = rs_from_ss(b_); cached_pm = cur.pm; }
.LBB0_661:
	s_and_b64 vcc, exec, s[38:39]
	s_cbranch_vccnz .Lrsl_pf_skip
	s_and_b64 vcc, exec, s[4:5]
	s_cbranch_vccnz .Lrsl_pf_skip
	s_cmp_eq_u32 s94, s95
	s_cbranch_scc1 .Lrsl_pf_skip
	s_lshl_b32 s10, s94, 8
	s_ashr_i32 s11, s10, 31
	v_lshl_add_u64 v[236:237], s[10:11], 2, v[182:183]
	global_load_dword v234, v[236:237], off
	global_load_dword v235, v[236:237], off offset:512

; __device__ __forceinline__ float rs_from_ss(float ss) { return rsqrtf(ss * (1.0f / DM) + RMS_EPS); }
; __device__ __forceinline__ void epilogue(const Epi& E, f32x4 (&acc)[2][2][4][2], const Unit& u, int wr, int wc, int fr, int fq, const LAS float* rsl) {
;     ...
;         f32x4 cs[2][2]; float rr[8];
; #pragma unroll
;         for (int i = 0; i < 8; ++i) rr[i] = rsl[(i >> 2) * 64 + (i & 3) * 16 + fr];
; #pragma unroll
;         for (int bj = 0; bj < 2; ++bj)
; #pragma unroll
;             for (int n = 0; n < 2; ++n) {
;                 cs[bj][n] = (f32x4){1.f, 1.f, 1.f, 1.f};
;                 if (E.mode == EPI_COLSCALE) { const f32x4 t = *(const f32x4*)(E.ss_in + col0 + bj * HALF + 4 * n);
; #pragma unroll
;                     for (int e = 0; e < 4; ++e) cs[bj][n][e] = rs_from_ss(t[e]); }
;             }
.LBB0_693:
	ds_read2_b32 v[152:153], v216 offset1:16
	ds_read2_b32 v[150:151], v216 offset0:32 offset1:48
	ds_read2_b32 v[146:147], v216 offset0:64 offset1:80
	s_waitcnt lgkmcnt(0)
	ds_read2_b32 v[130:131], v216 offset0:96 offset1:112
	v_ashrrev_i32_e32 v155, 31, v154
	v_mov_b32_e32 v132, 1.0
	v_cndmask_b32_e64 v133, 0, 1, s[96:97]
	v_lshl_add_u64 v[156:157], v[154:155], 2, s[66:67]
	v_cmp_ne_u32_e64 s[40:41], 1, v133
	s_andn2_b64 vcc, exec, s[96:97]
	v_mov_b32_e32 v134, 1.0
	v_mov_b32_e32 v135, v132
	v_mov_b32_e32 v136, 1.0
	v_mov_b32_e32 v137, 1.0
	s_cbranch_vccnz .LBB0_695
	global_load_dwordx4 v[134:137], v[156:157], off
	global_load_dwordx4 v[236:239], v[156:157], off offset:16
	global_load_dwordx4 v[240:243], v[156:157], off offset:512
	global_load_dwordx4 v[244:247], v[156:157], off offset:528
	s_mov_b32 s10, 0x358637bd
	v_mov_b64_e32 v[138:139], s[10:11]
	s_mov_b32 s10, 0x3a000000
	s_mov_b32 s22, 0x45800000
	s_waitcnt vmcnt(0)
	v_pk_fma_f32 v[134:135], v[134:135], s[10:11], v[138:139] op_sel_hi:[1,0,0]
	s_nop 0
	v_mul_f32_e32 v133, 0x4b800000, v134
	v_cmp_gt_f32_e64 s[42:43], s33, v134
	v_cmp_gt_f32_e32 vcc, s33, v135
	v_pk_fma_f32 v[136:137], v[136:137], s[10:11], v[138:139] op_sel_hi:[1,0,0]
	v_cndmask_b32_e64 v133, v134, v133, s[42:43]
	v_rsq_f32_e32 v134, v133
	v_mul_f32_e32 v133, 0x4b800000, v135
	v_cndmask_b32_e32 v133, v135, v133, vcc
	v_rsq_f32_e32 v135, v133
	v_mul_f32_e32 v133, 0x4b800000, v136
	v_pk_mul_f32 v[140:141], v[134:135], s[22:23] op_sel_hi:[1,0]
	s_nop 0
	v_cndmask_b32_e64 v134, v134, v140, s[42:43]
	v_cmp_gt_f32_e64 s[42:43], s33, v136
	v_cndmask_b32_e32 v135, v135, v141, vcc
	v_cmp_gt_f32_e32 vcc, s33, v137
	v_cndmask_b32_e64 v133, v136, v133, s[42:43]
	v_rsq_f32_e32 v136, v133
	v_mul_f32_e32 v133, 0x4b800000, v137
	v_cndmask_b32_e32 v133, v137, v133, vcc
	v_rsq_f32_e32 v137, v133
	s_nop 0
	v_pk_mul_f32 v[138:139], v[136:137], s[22:23] op_sel_hi:[1,0]
	s_nop 0
	v_cndmask_b32_e64 v136, v136, v138, s[42:43]
	v_cndmask_b32_e32 v137, v137, v139, vcc
.LBB0_695:
	s_and_b64 vcc, exec, s[40:41]
	v_mov_b32_e32 v133, 1.0
	v_mov_b32_e32 v142, 1.0
	v_mov_b32_e32 v143, 1.0
	s_cbranch_vccnz .LBB0_697
	v_mov_b64_e32 v[138:139], v[236:237]
	v_mov_b64_e32 v[140:141], v[238:239]
	s_mov_b32 s10, 0x358637bd
	v_mov_b64_e32 v[142:143], s[10:11]
	s_mov_b32 s10, 0x3a000000
	s_mov_b32 s22, 0x45800000
	s_waitcnt vmcnt(0)
	v_pk_fma_f32 v[132:133], v[138:139], s[10:11], v[142:143] op_sel_hi:[1,0,0]
	s_nop 0
	v_mul_f32_e32 v138, 0x4b800000, v132
	v_cmp_gt_f32_e64 s[42:43], s33, v132
	v_cmp_gt_f32_e32 vcc, s33, v133
	s_nop 0
	v_cndmask_b32_e64 v132, v132, v138, s[42:43]
	v_mul_f32_e32 v138, 0x4b800000, v133
	v_cndmask_b32_e32 v133, v133, v138, vcc
	v_rsq_f32_e32 v132, v132
	v_rsq_f32_e32 v133, v133
	s_nop 0
	v_pk_mul_f32 v[138:139], v[132:133], s[22:23] op_sel_hi:[1,0]
	s_nop 0
	v_cndmask_b32_e64 v132, v132, v138, s[42:43]
	v_cndmask_b32_e32 v133, v133, v139, vcc
	v_pk_fma_f32 v[138:139], v[140:141], s[10:11], v[142:143] op_sel_hi:[1,0,0]
	s_nop 0
	v_mul_f32_e32 v140, 0x4b800000, v138
	v_cmp_gt_f32_e64 s[42:43], s33, v138
	v_cmp_gt_f32_e32 vcc, s33, v139
	s_nop 0
	v_cndmask_b32_e64 v138, v138, v140, s[42:43]
	v_mul_f32_e32 v140, 0x4b800000, v139
	v_cndmask_b32_e32 v139, v139, v140, vcc
	v_rsq_f32_e32 v138, v138
	v_rsq_f32_e32 v139, v139
	s_nop 0
	v_pk_mul_f32 v[140:141], v[138:139], s[22:23] op_sel_hi:[1,0]
	s_nop 0
	v_cndmask_b32_e64 v142, v138, v140, s[42:43]
	v_cndmask_b32_e32 v143, v139, v141, vcc
.LBB0_697:
	v_mov_b32_e32 v138, 1.0
	s_and_b64 vcc, exec, s[40:41]
	v_mov_b32_e32 v140, 1.0
	v_mov_b32_e32 v141, 1.0
	v_mov_b32_e32 v144, 1.0
	v_mov_b32_e32 v145, 1.0
	s_cbranch_vccnz .LBB0_699
	v_mov_b64_e32 v[158:159], v[240:241]
	v_mov_b64_e32 v[160:161], v[242:243]
	s_mov_b32 s10, 0x358637bd
	v_mov_b64_e32 v[144:145], s[10:11]
	s_mov_b32 s10, 0x3a000000
	s_mov_b32 s22, 0x45800000
	s_waitcnt vmcnt(0)
	v_pk_fma_f32 v[140:141], v[158:159], s[10:11], v[144:145] op_sel_hi:[1,0,0]
	s_nop 0
	v_mul_f32_e32 v139, 0x4b800000, v140
	v_cmp_gt_f32_e64 s[42:43], s33, v140
	v_cmp_gt_f32_e32 vcc, s33, v141
	v_pk_fma_f32 v[144:145], v[160:161], s[10:11], v[144:145] op_sel_hi:[1,0,0]
	v_cndmask_b32_e64 v139, v140, v139, s[42:43]
	v_rsq_f32_e32 v140, v139
	v_mul_f32_e32 v139, 0x4b800000, v141
	v_cndmask_b32_e32 v139, v141, v139, vcc
	v_rsq_f32_e32 v141, v139
	v_mul_f32_e32 v139, 0x4b800000, v144
	v_pk_mul_f32 v[148:149], v[140:141], s[22:23] op_sel_hi:[1,0]
	s_nop 0
	v_cndmask_b32_e64 v140, v140, v148, s[42:43]
	v_cmp_gt_f32_e64 s[42:43], s33, v144
	v_cndmask_b32_e32 v141, v141, v149, vcc
	v_cmp_gt_f32_e32 vcc, s33, v145
	v_cndmask_b32_e64 v139, v144, v139, s[42:43]
	v_rsq_f32_e32 v144, v139
	v_mul_f32_e32 v139, 0x4b800000, v145
	v_cndmask_b32_e32 v139, v145, v139, vcc
	v_rsq_f32_e32 v145, v139
	s_nop 0
	v_pk_mul_f32 v[148:149], v[144:145], s[22:23] op_sel_hi:[1,0]
	s_nop 0
	v_cndmask_b32_e64 v144, v144, v148, s[42:43]
	v_cndmask_b32_e32 v145, v145, v149, vcc
.LBB0_699:
	s_and_b64 vcc, exec, s[40:41]
	v_mov_b32_e32 v139, 1.0
	v_mov_b32_e32 v148, 1.0
	v_mov_b32_e32 v149, 1.0
	s_cbranch_vccnz .LBB0_701
	v_mov_b64_e32 v[156:157], v[244:245]
	v_mov_b64_e32 v[158:159], v[246:247]
	s_mov_b32 s10, 0x358637bd
	v_mov_b64_e32 v[148:149], s[10:11]
	s_mov_b32 s10, 0x3a000000
	s_mov_b32 s22, 0x45800000
	s_waitcnt vmcnt(0)
	v_pk_fma_f32 v[138:139], v[156:157], s[10:11], v[148:149] op_sel_hi:[1,0,0]
	s_nop 0
	v_mul_f32_e32 v156, 0x4b800000, v138
	v_cmp_gt_f32_e64 s[40:41], s33, v138
	v_cmp_gt_f32_e32 vcc, s33, v139
	v_pk_fma_f32 v[148:149], v[158:159], s[10:11], v[148:149] op_sel_hi:[1,0,0]
	v_cndmask_b32_e64 v138, v138, v156, s[40:41]
	v_mul_f32_e32 v156, 0x4b800000, v139
	v_cndmask_b32_e32 v139, v139, v156, vcc
	v_rsq_f32_e32 v138, v138
	v_rsq_f32_e32 v139, v139
	s_nop 0
	v_pk_mul_f32 v[156:157], v[138:139], s[22:23] op_sel_hi:[1,0]
	s_nop 0
	v_cndmask_b32_e64 v138, v138, v156, s[40:41]
	v_mul_f32_e32 v156, 0x4b800000, v148
	v_cmp_gt_f32_e64 s[40:41], s33, v148
	v_cndmask_b32_e32 v139, v139, v157, vcc
	v_cmp_gt_f32_e32 vcc, s33, v149
	v_cndmask_b32_e64 v148, v148, v156, s[40:41]
	v_mul_f32_e32 v156, 0x4b800000, v149
	v_cndmask_b32_e32 v149, v149, v156, vcc
	v_rsq_f32_e32 v148, v148
	v_rsq_f32_e32 v149, v149
	s_nop 0
	v_pk_mul_f32 v[156:157], v[148:149], s[22:23] op_sel_hi:[1,0]
	s_nop 0
	v_cndmask_b32_e64 v148, v148, v156, s[40:41]
	v_cndmask_b32_e32 v149, v149, v157, vcc

; __device__ __forceinline__ float rs_from_ss(float ss) { return rsqrtf(ss * (1.0f / DM) + RMS_EPS); }
; __device__ __forceinline__ void gemm_phase(LAS unsigned char* lds, const Gemm g, const StaticOrder& S, const Epi& E) {
;     ...
;         if (rowss && cur.pm != cached_pm) { const float* sp = E.ss_in + cur.pm * BM + wr * 64 + lane; const float a_ = sp[0], b_ = sp[HALF]; rsl[lane] = rs_from_ss(a_); rsl[64 + lane] = rs_from_ss(b_); cached_pm = cur.pm; }
.LBB0_848:
	s_cmp_eq_u32 s94, s95
	s_cselect_b64 s[10:11], -1, 0
	s_or_b64 s[10:11], s[4:5], s[10:11]
	s_and_b64 vcc, exec, s[10:11]
	s_cbranch_vccnz .LBB0_850
	v_mov_b32_e32 v4, v234
	v_mov_b32_e32 v2, v235
	s_mov_b32 s95, s94
	v_fmamk_f32 v3, v4, 0x3a000000, v172
	v_cmp_gt_f32_e32 vcc, s33, v3
	v_mul_f32_e32 v4, 0x4b800000, v3
	v_fmamk_f32 v2, v2, 0x3a000000, v172
	v_cndmask_b32_e32 v3, v3, v4, vcc
	v_rsq_f32_e32 v3, v3
	s_nop 0
	v_mul_f32_e32 v4, 0x45800000, v3
	v_cndmask_b32_e32 v3, v3, v4, vcc
	v_cmp_gt_f32_e32 vcc, s33, v2
	v_mul_f32_e32 v4, 0x4b800000, v2
	s_nop 0
	v_cndmask_b32_e32 v2, v2, v4, vcc
	v_rsq_f32_e32 v2, v2
	s_nop 0
	v_mul_f32_e32 v4, 0x45800000, v2
	v_cndmask_b32_e32 v2, v2, v4, vcc
	ds_write2st64_b32 v220, v3, v2 offset1:1
